# v29 + single-counter fast path for the projection->mixers seam (arrival add without return, one load pair per look at the counter and the neighbour's progress word)
# baseline (speedup 1.0000x reference)
.LBB0_232:
	s_waitcnt lgkmcnt(0)
	v_cmp_eq_u32_e32 vcc, 1, v2
	s_cbranch_vccz .Ls0_slow
	v_readlane_b32 s4, v253, 37
	v_readlane_b32 s5, v253, 38
	v_readlane_b32 s11, v250, 21
	v_mov_b32_e32 v5, 1
	s_nop 2
	s_add_i32 s11, s11, 1
	v_mul_lo_u32 v6, v4, s11
	v_readlane_b32 s98, v252, 27
	v_readlane_b32 s99, v252, 28
	v_readlane_b32 s20, v252, 25
	v_readlane_b32 s21, v252, 26
	s_mov_b32 s11, 0
	s_nop 4
	global_atomic_add v27, v5, s[4:5]
.Ls0_poll:
	global_load_dword v7, v27, s[4:5] sc1
	s_cmp_eq_u64 s[20:21], 0
	s_cbranch_scc1 .Ls0_nonb
	global_load_dword v242, v27, s[98:99] sc1
	s_waitcnt vmcnt(0)
	v_cmp_lt_u32_e32 vcc, s75, v242
	s_cbranch_vccz .Ls0_again
.Ls0_nonb:
	s_waitcnt vmcnt(0)
	v_cmp_ge_u32_e32 vcc, v7, v6
	s_cbranch_vccnz .Ls0_rel
.Ls0_again:
	s_sleep 1
	s_add_i32 s11, s11, 1
	s_cmp_lt_u32 s11, 0x2000
	s_cbranch_scc1 .Ls0_poll
.Ls0_rel:
	s_mov_b64 s[20:21], 0
	v_readlane_b32 s4, v252, 31
	v_readlane_b32 s5, v252, 32
	s_andn2_b64 vcc, exec, s[4:5]
	s_cbranch_vccnz .LBB0_267
	v_readlane_b32 s4, v253, 39
	v_readlane_b32 s5, v253, 40
	s_nop 4
	global_atomic_add v27, v5, s[4:5]
	s_branch .LBB0_263
